# weight prep scaled item (second stage copy): norm-scale loads batched too
# baseline (speedup 1.0000x reference)
.LBB0_931:
	v_add_u32_e32 v16, 0x4a00, v112
	v_mov_b32_e32 v17, s37
	v_mov_b32_e32 v18, s28
	v_cmp_gt_i32_e32 vcc, s29, v16
	s_nop 1
	v_cndmask_b32_e32 v17, v17, v18, vcc
	v_add_u32_e32 v16, v17, v112
	v_add_u32_e32 v19, 0x4a00, v16
	v_cmp_lt_i32_e32 vcc, s59, v19
	s_and_saveexec_b64 s[6:7], vcc
	s_xor_b64 s[20:21], exec, s[6:7]
	s_cbranch_execz .LBB0_961
	s_movk_i32 s0, 0x43ff
	v_cmp_lt_u32_e32 vcc, s0, v19
	s_and_saveexec_b64 s[6:7], vcc
	s_xor_b64 s[6:7], exec, s[6:7]
	s_cbranch_execz .LBB0_946
	s_movk_i32 s0, 0x45ff
	v_cmp_lt_u32_e32 vcc, s0, v19
	s_and_saveexec_b64 s[8:9], vcc
	s_xor_b64 s[8:9], exec, s[8:9]
	s_cbranch_execz .LBB0_943
	s_movk_i32 s0, 0x47ff
	v_cmp_lt_u32_e32 vcc, s0, v19
	s_and_saveexec_b64 s[10:11], vcc
	s_xor_b64 s[10:11], exec, s[10:11]
	s_cbranch_execz .LBB0_940
	s_movk_i32 s0, 0x49ff
	v_cmp_lt_u32_e32 vcc, s0, v19
	s_and_saveexec_b64 s[22:23], vcc
	s_xor_b64 s[22:23], exec, s[22:23]
	s_cbranch_execz .LBB0_937
	s_mov_b32 s0, 0xaaaaaaab
	v_mul_hi_u32 v17, v16, s0
	s_load_dwordx2 s[50:51], s[92:93], 0x88
	s_load_dwordx2 s[24:25], s[92:93], 0x28
	v_lshrrev_b32_e32 v18, 6, v17
	s_movk_i32 s0, 0x60
	v_mul_lo_u32 v18, v18, s0
	v_sub_u32_e32 v18, v16, v18
	v_lshlrev_b32_e32 v158, 5, v18
	v_and_b32_e32 v16, 0xffffffc0, v17
	s_waitcnt lgkmcnt(0)
	v_lshl_add_u64 v[20:21], v[158:159], 2, s[50:51]
	v_lshlrev_b32_e32 v22, 2, v2
	v_mov_b32_e32 v23, v159
	v_or_b32_e32 v18, v16, v0
	v_lshl_add_u64 v[30:31], v[20:21], 0, v[22:23]
	s_movk_i32 s0, 0x3000
	v_mad_u64_u32 v[20:21], s[50:51], v18, s0, v[30:31]
	v_or_b32_e32 v17, 2, v18
	global_load_dword v34, v[20:21], off nt
	v_mad_u64_u32 v[20:21], s[50:51], v17, s0, v[30:31]
	v_or_b32_e32 v17, 4, v18
	global_load_dword v35, v[20:21], off nt
	v_mad_u64_u32 v[20:21], s[50:51], v17, s0, v[30:31]
	v_or_b32_e32 v17, 6, v18
	global_load_dword v36, v[20:21], off nt
	v_mad_u64_u32 v[20:21], s[50:51], v17, s0, v[30:31]
	v_or_b32_e32 v17, 8, v18
	global_load_dword v37, v[20:21], off nt
	v_mad_u64_u32 v[20:21], s[50:51], v17, s0, v[30:31]
	v_or_b32_e32 v17, 10, v18
	global_load_dword v38, v[20:21], off nt
	v_mad_u64_u32 v[20:21], s[50:51], v17, s0, v[30:31]
	v_or_b32_e32 v17, 12, v18
	global_load_dword v39, v[20:21], off nt
	v_mad_u64_u32 v[20:21], s[50:51], v17, s0, v[30:31]
	v_or_b32_e32 v17, 14, v18
	global_load_dword v40, v[20:21], off nt
	v_mad_u64_u32 v[20:21], s[50:51], v17, s0, v[30:31]
	v_or_b32_e32 v17, 16, v18
	global_load_dword v41, v[20:21], off nt
	v_mad_u64_u32 v[20:21], s[50:51], v17, s0, v[30:31]
	v_or_b32_e32 v17, 18, v18
	global_load_dword v113, v[20:21], off nt
	v_mad_u64_u32 v[20:21], s[50:51], v17, s0, v[30:31]
	v_or_b32_e32 v17, 20, v18
	global_load_dword v114, v[20:21], off nt
	v_mad_u64_u32 v[20:21], s[50:51], v17, s0, v[30:31]
	v_or_b32_e32 v17, 22, v18
	global_load_dword v115, v[20:21], off nt
	v_mad_u64_u32 v[20:21], s[50:51], v17, s0, v[30:31]
	v_or_b32_e32 v17, 24, v18
	global_load_dword v116, v[20:21], off nt
	v_mad_u64_u32 v[20:21], s[50:51], v17, s0, v[30:31]
	v_or_b32_e32 v17, 26, v18
	global_load_dword v117, v[20:21], off nt
	v_mad_u64_u32 v[20:21], s[50:51], v17, s0, v[30:31]
	v_or_b32_e32 v17, 28, v18
	global_load_dword v118, v[20:21], off nt
	v_mad_u64_u32 v[20:21], s[50:51], v17, s0, v[30:31]
	v_or_b32_e32 v17, 30, v18
	global_load_dword v119, v[20:21], off nt
	v_mad_u64_u32 v[20:21], s[50:51], v17, s0, v[30:31]
	v_or_b32_e32 v17, 32, v18
	global_load_dword v120, v[20:21], off nt
	v_mad_u64_u32 v[20:21], s[50:51], v17, s0, v[30:31]
	v_or_b32_e32 v17, 34, v18
	global_load_dword v121, v[20:21], off nt
	v_mad_u64_u32 v[20:21], s[50:51], v17, s0, v[30:31]
	v_or_b32_e32 v17, 36, v18
	global_load_dword v122, v[20:21], off nt
	v_mad_u64_u32 v[20:21], s[50:51], v17, s0, v[30:31]
	v_or_b32_e32 v17, 38, v18
	global_load_dword v123, v[20:21], off nt
	v_mad_u64_u32 v[20:21], s[50:51], v17, s0, v[30:31]
	v_or_b32_e32 v17, 40, v18
	global_load_dword v124, v[20:21], off nt
	v_mad_u64_u32 v[20:21], s[50:51], v17, s0, v[30:31]
	v_or_b32_e32 v17, 42, v18
	global_load_dword v125, v[20:21], off nt
	v_mad_u64_u32 v[20:21], s[50:51], v17, s0, v[30:31]
	v_or_b32_e32 v17, 44, v18
	global_load_dword v29, v[20:21], off nt
	v_mad_u64_u32 v[20:21], s[50:51], v17, s0, v[30:31]
	v_or_b32_e32 v17, 46, v18
	global_load_dword v28, v[20:21], off nt
	v_mad_u64_u32 v[20:21], s[50:51], v17, s0, v[30:31]
	v_or_b32_e32 v17, 48, v18
	global_load_dword v27, v[20:21], off nt
	v_mad_u64_u32 v[20:21], s[50:51], v17, s0, v[30:31]
	v_or_b32_e32 v17, 50, v18
	global_load_dword v26, v[20:21], off nt
	v_mad_u64_u32 v[20:21], s[50:51], v17, s0, v[30:31]
	v_or_b32_e32 v17, 52, v18
	global_load_dword v25, v[20:21], off nt
	v_mad_u64_u32 v[20:21], s[50:51], v17, s0, v[30:31]
	v_or_b32_e32 v17, 54, v18
	global_load_dword v24, v[20:21], off nt
	v_mad_u64_u32 v[20:21], s[50:51], v17, s0, v[30:31]
	v_or_b32_e32 v17, 56, v18
	s_add_u32 s24, s24, 0x1000
	global_load_dword v23, v[20:21], off nt
	v_mad_u64_u32 v[20:21], s[50:51], v17, s0, v[30:31]
	v_or_b32_e32 v17, 58, v18
	s_addc_u32 s25, s25, 0
	v_mov_b32_e32 v19, v159
	global_load_dword v22, v[20:21], off nt
	v_mad_u64_u32 v[20:21], s[50:51], v17, s0, v[30:31]
	v_or_b32_e32 v17, 60, v18
	v_mad_u64_u32 v[32:33], s[50:51], v17, s0, v[30:31]
	v_or_b32_e32 v17, 62, v18
	v_lshl_add_u64 v[18:19], v[18:19], 2, s[24:25]
	global_load_dword v214, v[18:19], off
	v_mov_b32_e32 v19, v159
	global_load_dword v21, v[20:21], off nt
	v_mad_u64_u32 v[30:31], s[50:51], v17, s0, v[30:31]
	global_load_dword v17, v[30:31], off nt
	global_load_dword v20, v[32:33], off nt
	v_or_b32_e32 v18, v16, v45
	v_lshl_add_u64 v[18:19], v[18:19], 2, s[24:25]
	global_load_dword v215, v[18:19], off
	v_mov_b32_e32 v19, v159
	v_or_b32_e32 v18, v16, v47
	v_lshl_add_u64 v[18:19], v[18:19], 2, s[24:25]
	global_load_dword v216, v[18:19], off
	v_mov_b32_e32 v19, v159
	v_or_b32_e32 v18, v16, v49
	v_lshl_add_u64 v[18:19], v[18:19], 2, s[24:25]
	global_load_dword v217, v[18:19], off
	v_mov_b32_e32 v19, v159
	v_or_b32_e32 v18, v16, v51
	v_lshl_add_u64 v[18:19], v[18:19], 2, s[24:25]
	global_load_dword v218, v[18:19], off
	v_mov_b32_e32 v19, v159
	v_or_b32_e32 v18, v16, v53
	v_lshl_add_u64 v[18:19], v[18:19], 2, s[24:25]
	global_load_dword v219, v[18:19], off
	v_mov_b32_e32 v19, v159
	v_or_b32_e32 v18, v16, v55
	v_lshl_add_u64 v[18:19], v[18:19], 2, s[24:25]
	global_load_dword v220, v[18:19], off
	v_mov_b32_e32 v19, v159
	v_or_b32_e32 v18, v16, v57
	v_lshl_add_u64 v[18:19], v[18:19], 2, s[24:25]
	global_load_dword v221, v[18:19], off
	v_mov_b32_e32 v19, v159
	v_or_b32_e32 v18, v16, v59
	v_lshl_add_u64 v[18:19], v[18:19], 2, s[24:25]
	global_load_dword v222, v[18:19], off
	v_mov_b32_e32 v19, v159
	v_or_b32_e32 v18, v16, v61
	v_lshl_add_u64 v[18:19], v[18:19], 2, s[24:25]
	global_load_dword v223, v[18:19], off
	v_mov_b32_e32 v19, v159
	v_or_b32_e32 v18, v16, v63
	v_lshl_add_u64 v[18:19], v[18:19], 2, s[24:25]
	global_load_dword v224, v[18:19], off
	v_mov_b32_e32 v19, v159
	v_or_b32_e32 v18, v16, v65
	v_lshl_add_u64 v[18:19], v[18:19], 2, s[24:25]
	global_load_dword v225, v[18:19], off
	v_mov_b32_e32 v19, v159
	v_or_b32_e32 v18, v16, v67
	v_lshl_add_u64 v[18:19], v[18:19], 2, s[24:25]
	global_load_dword v226, v[18:19], off
	v_mov_b32_e32 v19, v159
	v_or_b32_e32 v18, v16, v69
	v_lshl_add_u64 v[18:19], v[18:19], 2, s[24:25]
	global_load_dword v227, v[18:19], off
	v_mov_b32_e32 v19, v159
	v_or_b32_e32 v18, v16, v71
	v_lshl_add_u64 v[18:19], v[18:19], 2, s[24:25]
	global_load_dword v228, v[18:19], off
	v_mov_b32_e32 v19, v159
	v_or_b32_e32 v18, v16, v73
	v_lshl_add_u64 v[18:19], v[18:19], 2, s[24:25]
	global_load_dword v229, v[18:19], off
	v_mov_b32_e32 v19, v159
	s_waitcnt vmcnt(0)
	v_mul_f32_e32 v18, v34, v214
	ds_write_b32 v44, v18
	v_mul_f32_e32 v18, v35, v215
	ds_write_b32 v46, v18
	v_mul_f32_e32 v18, v36, v216
	ds_write_b32 v48, v18
	v_mul_f32_e32 v18, v37, v217
	ds_write_b32 v50, v18
	v_mul_f32_e32 v18, v38, v218
	ds_write_b32 v52, v18
	v_mul_f32_e32 v18, v39, v219
	ds_write_b32 v54, v18
	v_mul_f32_e32 v18, v40, v220
	ds_write_b32 v56, v18
	v_mul_f32_e32 v18, v41, v221
	ds_write_b32 v58, v18
	v_mul_f32_e32 v18, v113, v222
	ds_write_b32 v60, v18
	v_mul_f32_e32 v18, v114, v223
	ds_write_b32 v62, v18
	v_mul_f32_e32 v18, v115, v224
	ds_write_b32 v64, v18
	v_mul_f32_e32 v18, v116, v225
	ds_write_b32 v66, v18
	v_mul_f32_e32 v18, v117, v226
	ds_write_b32 v68, v18
	v_mul_f32_e32 v18, v118, v227
	ds_write_b32 v70, v18
	v_mul_f32_e32 v18, v119, v228
	ds_write_b32 v72, v18
	v_mul_f32_e32 v18, v120, v229
	ds_write_b32 v74, v18
	v_or_b32_e32 v18, v16, v75
	v_lshl_add_u64 v[18:19], v[18:19], 2, s[24:25]
	global_load_dword v230, v[18:19], off
	v_mov_b32_e32 v19, v159
	v_or_b32_e32 v18, v16, v77
	v_lshl_add_u64 v[18:19], v[18:19], 2, s[24:25]
	global_load_dword v231, v[18:19], off
	v_mov_b32_e32 v19, v159
	v_or_b32_e32 v18, v16, v79
	v_lshl_add_u64 v[18:19], v[18:19], 2, s[24:25]
	global_load_dword v232, v[18:19], off
	v_mov_b32_e32 v19, v159
	v_or_b32_e32 v18, v16, v81
	v_lshl_add_u64 v[18:19], v[18:19], 2, s[24:25]
	global_load_dword v233, v[18:19], off
	v_mov_b32_e32 v19, v159
	v_or_b32_e32 v18, v16, v83
	v_lshl_add_u64 v[18:19], v[18:19], 2, s[24:25]
	global_load_dword v234, v[18:19], off
	v_mov_b32_e32 v19, v159
	v_or_b32_e32 v18, v16, v85
	v_lshl_add_u64 v[18:19], v[18:19], 2, s[24:25]
	global_load_dword v235, v[18:19], off
	v_mov_b32_e32 v19, v159
	v_or_b32_e32 v18, v16, v87
	v_lshl_add_u64 v[18:19], v[18:19], 2, s[24:25]
	global_load_dword v236, v[18:19], off
	v_mov_b32_e32 v19, v159
	v_or_b32_e32 v18, v16, v89
	v_lshl_add_u64 v[18:19], v[18:19], 2, s[24:25]
	global_load_dword v237, v[18:19], off
	v_mov_b32_e32 v19, v159
	v_or_b32_e32 v18, v16, v91
	v_lshl_add_u64 v[18:19], v[18:19], 2, s[24:25]
	global_load_dword v238, v[18:19], off
	v_mov_b32_e32 v19, v159
	v_or_b32_e32 v18, v16, v93
	v_lshl_add_u64 v[18:19], v[18:19], 2, s[24:25]
	global_load_dword v239, v[18:19], off
	v_mov_b32_e32 v19, v159
	v_or_b32_e32 v18, v16, v95
	v_lshl_add_u64 v[18:19], v[18:19], 2, s[24:25]
	global_load_dword v240, v[18:19], off
	v_mov_b32_e32 v19, v159
	v_or_b32_e32 v18, v16, v97
	v_lshl_add_u64 v[18:19], v[18:19], 2, s[24:25]
	global_load_dword v241, v[18:19], off
	v_mov_b32_e32 v19, v159
	v_or_b32_e32 v18, v16, v99
	v_lshl_add_u64 v[18:19], v[18:19], 2, s[24:25]
	global_load_dword v242, v[18:19], off
	v_mov_b32_e32 v19, v159
	v_or_b32_e32 v18, v16, v101
	v_lshl_add_u64 v[18:19], v[18:19], 2, s[24:25]
	global_load_dword v243, v[18:19], off
	v_mov_b32_e32 v19, v159
	v_or_b32_e32 v18, v16, v103
	v_lshl_add_u64 v[18:19], v[18:19], 2, s[24:25]
	global_load_dword v244, v[18:19], off
	v_mov_b32_e32 v19, v159
	v_or_b32_e32 v18, v16, v105
	v_lshl_add_u64 v[18:19], v[18:19], 2, s[24:25]
	global_load_dword v245, v[18:19], off
	v_mov_b32_e32 v19, v159
	s_waitcnt vmcnt(0)
	v_mul_f32_e32 v18, v121, v230
	ds_write_b32 v76, v18
	v_mul_f32_e32 v18, v122, v231
	ds_write_b32 v78, v18
	v_mul_f32_e32 v18, v123, v232
	ds_write_b32 v80, v18
	v_mul_f32_e32 v18, v124, v233
	ds_write_b32 v82, v18
	v_mul_f32_e32 v18, v125, v234
	ds_write_b32 v84, v18
	v_mul_f32_e32 v18, v29, v235
	ds_write_b32 v86, v18
	v_mul_f32_e32 v18, v28, v236
	ds_write_b32 v88, v18
	v_mul_f32_e32 v18, v27, v237
	ds_write_b32 v90, v18
	v_mul_f32_e32 v18, v26, v238
	ds_write_b32 v92, v18
	v_mul_f32_e32 v18, v25, v239
	ds_write_b32 v94, v18
	v_mul_f32_e32 v18, v24, v240
	ds_write_b32 v96, v18
	v_mul_f32_e32 v18, v23, v241
	ds_write_b32 v98, v18
	v_mul_f32_e32 v18, v22, v242
	ds_write_b32 v100, v18
	v_mul_f32_e32 v18, v21, v243
	ds_write_b32 v102, v18
	v_mul_f32_e32 v18, v20, v244
	ds_write_b32 v104, v18
	v_mul_f32_e32 v17, v17, v245
	ds_write_b32 v106, v17
	v_mov_b32_e32 v17, v159
	s_waitcnt lgkmcnt(0)
	v_lshl_add_u64 v[20:21], v[16:17], 1, v[6:7]
	ds_read2_b32 v[16:17], v108 offset1:33
	s_waitcnt lgkmcnt(0)
	v_cvt_pk_bf16_f32 v16, v16, v17
	ds_read2_b32 v[18:19], v108 offset0:66 offset1:99
	s_waitcnt lgkmcnt(0)
	v_cvt_pk_bf16_f32 v17, v18, v19
	ds_read2_b32 v[18:19], v108 offset0:132 offset1:165
	s_waitcnt lgkmcnt(0)
	v_cvt_pk_bf16_f32 v18, v18, v19
	ds_read2_b32 v[22:23], v108 offset0:198 offset1:231
	s_waitcnt lgkmcnt(0)
	v_cvt_pk_bf16_f32 v19, v22, v23
	v_or_b32_e32 v22, v158, v107
	v_lshlrev_b32_e32 v22, 11, v22
	v_mov_b32_e32 v23, v159
	v_lshl_add_u64 v[22:23], v[20:21], 0, v[22:23]
	global_store_dwordx4 v[22:23], v[16:19], off
	ds_read2_b32 v[16:17], v108 offset0:8 offset1:41
	s_waitcnt lgkmcnt(0)
	v_cvt_pk_bf16_f32 v16, v16, v17
	ds_read2_b32 v[18:19], v108 offset0:74 offset1:107
	s_waitcnt lgkmcnt(0)
	v_cvt_pk_bf16_f32 v17, v18, v19
	ds_read2_b32 v[18:19], v108 offset0:140 offset1:173
	s_waitcnt lgkmcnt(0)
	v_cvt_pk_bf16_f32 v18, v18, v19
	ds_read2_b32 v[22:23], v108 offset0:206 offset1:239
	s_waitcnt lgkmcnt(0)
	v_cvt_pk_bf16_f32 v19, v22, v23
	v_or_b32_e32 v22, v158, v109
	v_lshlrev_b32_e32 v22, 11, v22
	v_mov_b32_e32 v23, v159
	v_lshl_add_u64 v[22:23], v[20:21], 0, v[22:23]
	global_store_dwordx4 v[22:23], v[16:19], off
	ds_read2_b32 v[16:17], v108 offset0:16 offset1:49
	s_waitcnt lgkmcnt(0)
	v_cvt_pk_bf16_f32 v16, v16, v17
	ds_read2_b32 v[18:19], v108 offset0:82 offset1:115
	s_waitcnt lgkmcnt(0)
	v_cvt_pk_bf16_f32 v17, v18, v19
	ds_read2_b32 v[18:19], v108 offset0:148 offset1:181
	s_waitcnt lgkmcnt(0)
	v_cvt_pk_bf16_f32 v18, v18, v19
	ds_read2_b32 v[22:23], v108 offset0:214 offset1:247
	s_waitcnt lgkmcnt(0)
	v_cvt_pk_bf16_f32 v19, v22, v23
	v_or_b32_e32 v22, v158, v110
	v_lshlrev_b32_e32 v22, 11, v22
	v_mov_b32_e32 v23, v159
	v_lshl_add_u64 v[22:23], v[20:21], 0, v[22:23]
	global_store_dwordx4 v[22:23], v[16:19], off
	ds_read2_b32 v[16:17], v108 offset0:24 offset1:57
	s_waitcnt lgkmcnt(0)
	v_cvt_pk_bf16_f32 v16, v16, v17
	ds_read2_b32 v[18:19], v108 offset0:90 offset1:123
	s_waitcnt lgkmcnt(0)
	v_cvt_pk_bf16_f32 v17, v18, v19
	ds_read2_b32 v[18:19], v108 offset0:156 offset1:189
	s_waitcnt lgkmcnt(0)
	v_cvt_pk_bf16_f32 v18, v18, v19
	ds_read2_b32 v[22:23], v108 offset0:222 offset1:255
	s_waitcnt lgkmcnt(0)
	v_cvt_pk_bf16_f32 v19, v22, v23
	v_or_b32_e32 v22, v158, v111
	v_lshlrev_b32_e32 v158, 11, v22
	v_lshl_add_u64 v[20:21], v[20:21], 0, v[158:159]
	global_store_dwordx4 v[20:21], v[16:19], off
	s_waitcnt lgkmcnt(0)
